# guarded XCD-local release at the 7->8 and 15->16 barriers (expert tiles stay on one XCD under the remap; placement verified through the 0->1 counter)
# speedup vs baseline: 1.0071x; 1.0025x over previous
.LBB0_66:
	s_cmp_eq_u32 s99, 1
	s_cbranch_scc1 .Lp0_arr_done_a
	s_mov_b32 s99, 1
	s_waitcnt vmcnt(0)
	s_barrier
	s_mov_b64 s[12:13], exec
	v_readlane_b32 s38, v197, 0
	v_readlane_b32 s39, v197, 1
	s_and_b64 s[38:39], s[12:13], s[38:39]
	s_mov_b64 exec, s[38:39]
	s_cbranch_execz .Lp0_arr_m_a
	v_readlane_b32 s38, v197, 50
	s_and_b32 s39, s96, 7
	s_cmp_lg_u32 s38, s39
	s_cselect_b32 s38, 0x10001, 1
	v_mov_b32_e32 v251, 0
	v_mov_b32_e32 v252, s38
	global_atomic_add v251, v252, s[92:93] offset:160

.LBB0_108:
	s_cmp_eq_u32 s99, 1
	s_cbranch_scc1 .Lp0_arr_done_b
	s_mov_b32 s99, 1
	s_waitcnt vmcnt(0)
	s_barrier
	s_mov_b64 s[4:5], exec
	v_readlane_b32 s12, v197, 0
	v_readlane_b32 s13, v197, 1
	s_and_b64 s[12:13], s[4:5], s[12:13]
	s_mov_b64 exec, s[12:13]
	s_cbranch_execz .Lp0_arr_m_b
	v_readlane_b32 s12, v197, 50
	s_and_b32 s13, s96, 7
	s_cmp_lg_u32 s12, s13
	s_cselect_b32 s12, 0x10001, 1
	v_mov_b32_e32 v251, 0
	v_mov_b32_e32 v252, s12
	global_atomic_add v251, v252, s[92:93] offset:160

.Lp0_spin:
	global_load_dword v2, v1, s[92:93] offset:160 sc1
	s_waitcnt vmcnt(0)
	v_and_b32_e32 v251, 0xffff, v2
	v_cmp_le_u32_e32 vcc, s66, v251
	s_cbranch_vccnz .Lp0_out
	s_sleep 1
	s_branch .Lp0_spin

.LBB0_874:
	s_andn2_saveexec_b64 s[4:5], s[4:5]
	s_cbranch_execz .LBB0_894
	s_mov_b64 s[4:5], exec
	v_mov_b32_e32 v251, 0
	global_load_dword v252, v251, s[92:93] offset:160 sc1
	s_waitcnt vmcnt(0)
	v_readfirstlane_b32 s6, v252
	s_lshr_b32 s6, s6, 16
	s_cmp_lg_u32 s6, 0
	s_cbranch_scc1 .Lxl_slow_0
	s_cmp_lg_u32 s46, 0x100
	s_cbranch_scc1 .Lxl_slow_0
	v_mov_b32_e32 v251, 0x2000
	v_mov_b32_e32 v252, 1
	global_atomic_add v251, v252, s[2:3] offset:1024
	s_waitcnt vmcnt(0)
	buffer_inv sc1
	s_waitcnt vmcnt(0)
	s_branch .LBB0_894
.Lxl_slow_0:
	buffer_wbl2 sc1
	s_waitcnt lgkmcnt(0)
	s_waitcnt vmcnt(0)
	v_mbcnt_lo_u32_b32 v2, s4, 0
	v_mbcnt_hi_u32_b32 v2, s5, v2
	v_cmp_eq_u32_e32 vcc, 0, v2
	s_and_saveexec_b64 s[6:7], vcc
	s_cbranch_execz .LBB0_877
	s_bcnt1_i32_b64 s4, s[4:5]
	v_mov_b32_e32 v3, 0x3000
	v_mov_b32_e32 v4, s4
	global_atomic_add v3, v3, v4, s[92:93] offset:1024 sc0

.LBB0_1471:
	s_andn2_saveexec_b64 s[6:7], s[6:7]
	s_cbranch_execz .LBB0_1491
	s_mov_b64 s[6:7], exec
	v_mov_b32_e32 v251, 0
	global_load_dword v252, v251, s[92:93] offset:160 sc1
	s_waitcnt vmcnt(0)
	v_readfirstlane_b32 s8, v252
	s_lshr_b32 s8, s8, 16
	s_cmp_lg_u32 s8, 0
	s_cbranch_scc1 .Lxl_slow_1
	s_cmp_lg_u32 s46, 0x100
	s_cbranch_scc1 .Lxl_slow_1
	v_mov_b32_e32 v251, 0x2000
	v_mov_b32_e32 v252, 1
	global_atomic_add v251, v252, s[4:5] offset:1024
	s_waitcnt vmcnt(0)
	buffer_inv sc1
	s_waitcnt vmcnt(0)
	s_branch .LBB0_1491
.Lxl_slow_1:
	buffer_wbl2 sc1
	s_waitcnt lgkmcnt(0)
	s_waitcnt vmcnt(0)
	v_mbcnt_lo_u32_b32 v2, s6, 0
	v_mbcnt_hi_u32_b32 v2, s7, v2
	v_cmp_eq_u32_e32 vcc, 0, v2
	s_and_saveexec_b64 s[8:9], vcc
	s_cbranch_execz .LBB0_1474
	s_bcnt1_i32_b64 s6, s[6:7]
	v_mov_b32_e32 v3, 0x3000
	v_mov_b32_e32 v4, s6
	global_atomic_add v3, v3, v4, s[92:93] offset:1024 sc0
